# last grid barrier: no L2 write-back when every bx%8 class sits on one XCC (layer-1 gate/up outputs are consumed on the XCC that produced them)
# speedup vs baseline: 1.0116x; 1.0116x over previous
_Z8mega_fwd6Params:
	s_mov_b64 s[82:83], s[0:1]
	s_load_dwordx2 s[74:75], s[0:1], 0xb8
	s_load_dword s69, s[0:1], 0xc0
	v_and_b32_e32 v1, 0x3ff, v0
	s_mov_b32 s0, 0
	s_add_u32 s18, s82, 0xb8
	v_readfirstlane_b32 s68, v1
	s_addc_u32 s19, s83, 0
	v_mbcnt_lo_u32_b32 v2, -1, s0
	v_mbcnt_hi_u32_b32 v2, -1, v2
	s_and_b32 s72, s68, 0xffffffc0
	v_add_u32_e32 v3, s72, v2
	s_mov_b32 s93, s2
	v_cmp_gt_i32_e32 vcc, 2, v3
	s_and_saveexec_b64 s[4:5], vcc
	v_lshl_add_u32 v3, v3, 2, 0
	v_add_u32_e32 v3, 0x25000, v3
	v_mov_b32_e32 v4, 0
	ds_write_b32 v3, v4
	s_or_b64 exec, exec, s[4:5]
	s_load_dwordx2 s[4:5], s[82:83], 0xb0
	s_cmp_lt_u32 s68, 64
	s_cselect_b64 s[70:71], -1, 0
	v_cmp_eq_u32_e32 vcc, 0, v2
	s_and_b64 s[2:3], s[70:71], vcc
	s_getreg_b32 s0, hwreg(HW_REG_XCC_ID, 0, 4)
	s_and_saveexec_b64 s[6:7], s[2:3]
	s_cbranch_execz .LBB0_5
	s_mov_b64 s[8:9], exec
	v_mbcnt_lo_u32_b32 v2, s8, 0
	v_mbcnt_hi_u32_b32 v2, s9, v2
	v_cmp_eq_u32_e32 vcc, 0, v2
	s_and_b64 s[2:3], exec, vcc
	s_mov_b64 exec, s[2:3]
	s_cbranch_execz .LBB0_5
	s_lshl_b32 s0, s0, 8
	s_and_b32 s0, s0, 0xf00
	s_bcnt1_i32_b64 s1, s[8:9]
	v_mov_b32_e32 v2, s0
	v_mov_b32_e32 v3, s1
	s_waitcnt lgkmcnt(0)
	global_atomic_add v2, v3, s[4:5] offset:1024
	s_lshr_b32 s2, s0, 8
	s_lshl_b32 s2, 1, s2
	s_and_b32 s3, s93, 7
	s_lshl_b32 s3, s3, 2
	s_add_u32 s3, s3, 0x3a00
	v_mov_b32_e32 v4, s3
	v_mov_b32_e32 v5, s2
	global_atomic_or v4, v5, s[4:5]

.LBB0_1294:
	s_waitcnt lgkmcnt(0)
	v_readfirstlane_b32 s1, v2
	v_readfirstlane_b32 s10, v0
	s_lshl_b32 s0, s0, 8
	s_add_u32 s8, s6, s0
	s_addc_u32 s9, s7, 0
	v_mov_b32_e32 v3, 0x1000
	v_mov_b32_e32 v4, 1
	v_mov_b32_e32 v0, 0x2000
	global_atomic_add v3, v3, v4, s[8:9] offset:1024 sc0
	s_mul_i32 s1, s1, 13
	s_mul_i32 s10, s10, 13
	s_mov_b32 s13, 0
	s_waitcnt vmcnt(0)
	v_readfirstlane_b32 s11, v3
	s_add_u32 s11, s11, 1
	s_cmp_lg_u32 s11, s1
	s_cbranch_scc1 .Lxb12_wait
	v_mov_b32_e32 v6, 0x3a00
	global_load_dwordx4 v[8:11], v6, s[6:7] sc1
	global_load_dwordx4 v[12:15], v6, s[6:7] offset:16 sc1
	v_mov_b32_e32 v16, 0
	v_mov_b32_e32 v17, -1
	s_waitcnt vmcnt(0)
	v_add_u32_e32 v7, -1, v8
	v_and_b32_e32 v7, v7, v8
	v_or_b32_e32 v16, v16, v7
	v_min_u32_e32 v17, v17, v8
	v_add_u32_e32 v7, -1, v9
	v_and_b32_e32 v7, v7, v9
	v_or_b32_e32 v16, v16, v7
	v_min_u32_e32 v17, v17, v9
	v_add_u32_e32 v7, -1, v10
	v_and_b32_e32 v7, v7, v10
	v_or_b32_e32 v16, v16, v7
	v_min_u32_e32 v17, v17, v10
	v_add_u32_e32 v7, -1, v11
	v_and_b32_e32 v7, v7, v11
	v_or_b32_e32 v16, v16, v7
	v_min_u32_e32 v17, v17, v11
	v_add_u32_e32 v7, -1, v12
	v_and_b32_e32 v7, v7, v12
	v_or_b32_e32 v16, v16, v7
	v_min_u32_e32 v17, v17, v12
	v_add_u32_e32 v7, -1, v13
	v_and_b32_e32 v7, v7, v13
	v_or_b32_e32 v16, v16, v7
	v_min_u32_e32 v17, v17, v13
	v_add_u32_e32 v7, -1, v14
	v_and_b32_e32 v7, v7, v14
	v_or_b32_e32 v16, v16, v7
	v_min_u32_e32 v17, v17, v14
	v_add_u32_e32 v7, -1, v15
	v_and_b32_e32 v7, v7, v15
	v_or_b32_e32 v16, v16, v7
	v_min_u32_e32 v17, v17, v15
	s_nop 0
	v_readfirstlane_b32 s12, v16
	v_readfirstlane_b32 s13, v17
	s_cmp_lg_u32 s12, 0
	s_cbranch_scc1 .Lxb12_dowbl2
	s_cmp_lg_u32 s13, 0
	s_mov_b32 s13, 0
	s_cbranch_scc1 .Lxb12_nowbl2
.Lxb12_dowbl2:
	s_mov_b32 s13, 0
	buffer_wbl2 sc1
.Lxb12_nowbl2:
	buffer_inv sc1
	s_waitcnt vmcnt(0)
	v_mov_b32_e32 v3, 0x3000
	global_atomic_add v3, v3, v4, s[6:7] offset:1024 sc0
	s_waitcnt vmcnt(0)
	v_readfirstlane_b32 s11, v3
	s_add_u32 s11, s11, 1
	s_cmp_lg_u32 s11, s10
	s_cbranch_scc1 .Lxb12_poll
	v_mov_b32_e32 v5, 0x3000
	global_atomic_add v0, v4, s[6:7] offset:1024
	global_atomic_add v0, v4, s[6:7] offset:1280
	global_atomic_add v0, v4, s[6:7] offset:1536
	global_atomic_add v0, v4, s[6:7] offset:1792
	global_atomic_add v0, v4, s[6:7] offset:2048
	global_atomic_add v0, v4, s[6:7] offset:2304
	global_atomic_add v0, v4, s[6:7] offset:2560
	global_atomic_add v0, v4, s[6:7] offset:2816
	global_atomic_add v0, v4, s[6:7] offset:3072
	global_atomic_add v0, v4, s[6:7] offset:3328
	global_atomic_add v0, v4, s[6:7] offset:3584
	global_atomic_add v0, v4, s[6:7] offset:3840
	global_atomic_add v5, v4, s[6:7]
	global_atomic_add v5, v4, s[6:7] offset:256
	global_atomic_add v5, v4, s[6:7] offset:512
	global_atomic_add v5, v4, s[6:7] offset:768
	s_waitcnt vmcnt(0)
	s_branch .Lxb12_done
